# P3 prompt-tile-first + early decode units on workgroups 208-255
# speedup vs baseline: 1.0039x; 1.0039x over previous
; __device__ __forceinline__ int fresh_lane() { int l; asm volatile("v_mbcnt_lo_u32_b32 %0, -1, 0\n\tv_mbcnt_hi_u32_b32 %0, -1, %0" : "=v"(l)); return l; }
; #define SEAM(k) do { if (IN(k) && IN((k) + 1)) xcd_barrier(bar, C.wave); } while (0)
; #define PH5 { phase_attention(P, C, (P.pad >> 8) & 3, P.li); }
; #define RUN(k, BODY) do { if (IN(k)) { unsigned char* ws = P.ws; LAUNDER_GPTR(ws); BODY } } while (0)
; __device__ __forceinline__ void phase_attention(const Params& P, const Ctx& C, int parts, int qset) {
;     ...
;     for (int i = 0; i < 8; ++i) { const int x = (x0 + i) & 7;
;         for (;;) {
;             __syncthreads();
;             if (C.wave == 0 && fresh_lane() == 0) *slot = __hip_atomic_fetch_add(qc + 64 * x, 1u, __ATOMIC_RELAXED, __HIP_MEMORY_SCOPE_AGENT);
;             __syncthreads();
;             const unsigned u = *slot;
;             if (u >= 128u) break;
;             const int us = __builtin_amdgcn_readfirstlane((int)u);
; __global__ void __launch_bounds__(NWAVES * 64, 2) fwd_kernel(Params P) {
;     ...
;     RUN(3, PH3); SEAM(3);
;     RUN(4, PH4);
;     RUN(5, PH5); SEAM(5);
.LBB0_1136:
	s_bitcmp1_b32 s101, 1
	s_cbranch_scc1 .Lmy_e7
	s_bitset1_b32 s101, 1
	s_cmpk_lg_i32 s68, 0x100
	s_cbranch_scc1 .Lmy_e7
	s_bitset1_b32 s101, 3
	v_readlane_b32 s99, v254, 10
	s_cmpk_lt_u32 s99, 208
	s_cbranch_scc1 .Lmy_e7
	s_and_b32 s100, s99, 31
	s_mul_i32 s100, s100, 4
	s_add_i32 s100, s100, 1
	s_bitset1_b32 s101, 0
	s_waitcnt vmcnt(0)
	s_barrier
	s_mov_b64 s[2:3], -1
	s_branch .LBB0_1192

; __device__ __forceinline__ void phase_attention(const Params& P, const Ctx& C, int parts, int qset) {
;     ...
;             if (pq >= 0) { if (parts & 1) { if (fixed_ok) attn_prompt_unit<true>(P, C, x, pq); else attn_prompt_unit<false>(P, C, x, pq); } }
;             else { if (parts & 2) attn_decode_unit(P, C, x * 64 + dq); }
.LBB0_1215:
	s_bitcmp1_b32 s101, 0
	s_cbranch_scc1 .Lmy_e8
	s_bitcmp1_b32 s101, 3
	s_cbranch_scc0 .Lmy_e8
	v_readlane_b32 s99, v254, 13
	s_add_i32 s99, s99, s4
	s_cmpk_lt_u32 s99, 416
	s_cbranch_scc1 .Lmy_e8
	s_bitcmp0_b32 s4, 0
	s_cbranch_scc1 .LBB0_1200
